# hgrn_b3: the scan's bf16 superchunk start states (written in the previous phase, read once, full lines) are loaded with the nt hint; on top of the other nt read-once loads
# speedup vs baseline: 1.0125x; 1.0002x over previous
; #define GAS __attribute__((address_space(1)))
; #define WG_BAR() asm volatile("s_waitcnt lgkmcnt(0)\n\ts_barrier" ::: "memory")
; __device__ __forceinline__ void hgrn_b3(Frame& F, float* rso) {
;     ...
;     for (int it = F.bid; it < 512; it += F.G) {
;         const int bh = it >> 4, j = it & 15, b = bh >> 3, h = bh & 7; const size_t grow0 = (size_t)b * SEQ + j * 256;
;         WG_BAR();
;         v4u stq[8], sts[4];
; #pragma unroll
;         for (int i = 0; i < 8; ++i) { const int ch = tid + 512 * i, row = ch >> 4, c16 = ch & 15; stq[i] = *(const GAS v4u*)(Q2 + (grow0 + row) * DM + h * 128 + c16 * 8); }
; #pragma unroll
;         for (int i = 0; i < 4; ++i) { const int ch = tid + 512 * i, row = ch >> 4, c16 = ch & 15; sts[i] = *(const GAS v4u*)(SS + (size_t)it * 16384 + row * 128 + c16 * 8); }
;         v2u olr[2][8], ggr[2][8];
; #pragma unroll
;         for (int mi = 0; mi < 2; ++mi) { const int t = 32 * w + 16 * mi + r; const size_t rowoff = (grow0 + t) * DM + h * 128;
; #pragma unroll
;             for (int tn = 0; tn < 8; ++tn) { olr[mi][tn] = *(const GAS v2u*)(OL + rowoff + 16 * tn + 4 * g); ggr[mi][tn] = *(const GAS v2u*)(GH + wt_off((int)(grow0 + t), h * 128 + 16 * tn + 4 * g, DM)); } }
.LBB0_823:
	s_ashr_i32 s4, s27, 7
	s_ashr_i32 s5, s4, 31
	s_lshl_b64 s[20:21], s[4:5], 12
	s_and_b32 s4, s22, 0xf00
	s_or_b32 s20, s20, s4
	s_and_b32 s4, s1, 0x380
	s_lshl_b32 s16, s4, 1
	s_waitcnt lgkmcnt(0)
	v_lshl_add_u64 v[2:3], s[20:21], 0, v[28:29]
	v_lshl_add_u64 v[4:5], s[20:21], 0, v[30:31]
	v_lshl_add_u64 v[10:11], s[20:21], 0, v[32:33]
	v_lshl_add_u64 v[12:13], s[20:21], 0, v[34:35]
	v_lshl_add_u64 v[58:59], s[20:21], 0, v[36:37]
	v_lshl_add_u64 v[56:57], v[20:21], 0, s[16:17]
	v_lshlrev_b64 v[2:3], 11, v[2:3]
	v_lshlrev_b64 v[4:5], 11, v[4:5]
	v_lshlrev_b64 v[10:11], 11, v[10:11]
	v_lshlrev_b64 v[12:13], 11, v[12:13]
	v_lshlrev_b64 v[58:59], 11, v[58:59]
	v_lshl_add_u64 v[60:61], s[20:21], 0, v[38:39]
	s_waitcnt lgkmcnt(0)
	s_barrier
	v_lshl_add_u64 v[2:3], v[56:57], 0, v[2:3]
	v_lshl_add_u64 v[6:7], v[56:57], 0, v[4:5]
	v_lshl_add_u64 v[10:11], v[56:57], 0, v[10:11]
	v_lshl_add_u64 v[14:15], v[56:57], 0, v[12:13]
	v_lshl_add_u64 v[58:59], v[56:57], 0, v[58:59]
	v_lshlrev_b64 v[60:61], 11, v[60:61]
	global_load_dwordx4 v[2:5], v[2:3], off nt
	s_nop 0
	global_load_dwordx4 v[6:9], v[6:7], off nt
	s_nop 0
	global_load_dwordx4 v[10:13], v[10:11], off nt
	s_nop 0
	global_load_dwordx4 v[14:17], v[14:15], off nt
	v_lshl_add_u64 v[60:61], v[56:57], 0, v[60:61]
	global_load_dwordx4 v[152:155], v[58:59], off
	global_load_dwordx4 v[156:159], v[60:61], off
	v_lshl_add_u64 v[58:59], s[20:21], 0, v[40:41]
	v_lshlrev_b64 v[58:59], 11, v[58:59]
	v_lshl_add_u64 v[60:61], s[20:21], 0, v[42:43]
	v_lshl_add_u64 v[58:59], v[56:57], 0, v[58:59]
	v_lshlrev_b64 v[60:61], 11, v[60:61]
	v_lshl_add_u64 v[56:57], v[56:57], 0, v[60:61]
	global_load_dwordx4 v[162:165], v[58:59], off
	global_load_dwordx4 v[166:169], v[56:57], off
	v_lshl_add_u64 v[56:57], v[48:49], 0, v[46:47]
	v_lshl_add_u64 v[58:59], v[48:49], 0, v[50:51]
	global_load_dwordx4 v[170:173], v[56:57], off
	global_load_dwordx4 v[174:177], v[58:59], off
	v_lshl_add_u64 v[56:57], v[48:49], 0, v[52:53]
	v_lshl_add_u64 v[58:59], v[48:49], 0, v[54:55]
	global_load_dwordx4 v[178:181], v[56:57], off
	global_load_dwordx4 v[182:185], v[58:59], off
	v_lshl_add_u64 v[56:57], s[20:21], 0, v[22:23]
	v_lshl_add_u64 v[58:59], v[26:27], 0, s[16:17]
	v_lshlrev_b64 v[60:61], 11, v[56:57]
	v_lshl_add_u64 v[62:63], v[58:59], 0, v[60:61]
	v_ashrrev_i32_e32 v60, 8, v56
	v_ashrrev_i32_e32 v61, 31, v60
	v_lshlrev_b64 v[60:61], 19, v[60:61]
	v_lshlrev_b32_e32 v66, 7, v56
	v_lshlrev_b32_e32 v57, 6, v56
	v_lshlrev_b32_e32 v56, 2, v56
	v_or_b32_e32 v78, s4, v128
	v_and_b32_e32 v18, 0x4000, v66
	v_and_b32_e32 v76, 0x3c0, v57
	v_and_b32_e32 v77, 32, v56
	v_lshl_add_u64 v[56:57], s[12:13], 0, v[60:61]
	v_lshlrev_b32_e32 v150, 9, v78
	v_lshl_add_u64 v[64:65], v[56:57], 0, v[18:19]
	v_and_b32_e32 v18, 0x70000, v150
	v_or_b32_e32 v56, v76, v130
	v_and_b32_e32 v79, 0x3800, v66
	v_bitop3_b32 v149, v24, 56, 32 bitop3:0xc8
	v_and_b32_e32 v148, 24, v24
	v_or3_b32 v56, v56, v77, v79
	v_mov_b32_e32 v57, v19
	v_lshl_add_u64 v[60:61], v[64:65], 0, v[18:19]
	v_bitop3_b32 v74, v76, v77, v149 bitop3:0x36
	v_or_b32_e32 v70, v76, v148
	v_or_b32_e32 v80, 0x400, v79
	v_lshl_add_u64 v[66:67], v[60:61], 0, v[56:57]
	v_or_b32_e32 v68, v74, v79
	v_mov_b32_e32 v69, v19
	v_or3_b32 v70, v70, v77, v80
	v_mov_b32_e32 v71, v19
	global_load_dwordx2 v[116:117], v[62:63], off
	global_load_dwordx2 v[124:125], v[62:63], off offset:32
	global_load_dwordx2 v[118:119], v[62:63], off offset:64
	global_load_dwordx2 v[110:111], v[62:63], off offset:96
	v_or_b32_e32 v74, v74, v80
	v_mov_b32_e32 v75, v19
	v_lshl_add_u64 v[68:69], v[60:61], 0, v[68:69]
	v_lshl_add_u64 v[72:73], v[60:61], 0, v[70:71]
	v_lshl_add_u64 v[60:61], v[60:61], 0, v[74:75]
	global_load_dwordx2 v[122:123], v[66:67], off
	global_load_dwordx2 v[126:127], v[68:69], off
	global_load_dwordx2 v[120:121], v[72:73], off
	global_load_dwordx2 v[112:113], v[60:61], off
	v_or_b32_e32 v60, s4, v135
	v_lshlrev_b32_e32 v60, 9, v60
	v_and_b32_e32 v66, 0x78000, v60
	v_mov_b32_e32 v67, v19
	v_lshl_add_u64 v[60:61], v[64:65], 0, v[66:67]
	v_lshl_add_u64 v[68:69], v[60:61], 0, v[56:57]
	v_or_b32_e32 v56, 0x50, v78
	v_lshlrev_b32_e32 v57, 9, v56
	v_lshlrev_b32_e32 v56, 1, v56
	v_and_b32_e32 v145, 56, v56
	v_and_b32_e32 v60, 0x78000, v57
	v_mov_b32_e32 v61, v19
	v_bitop3_b32 v56, v76, v77, v145 bitop3:0x36
	s_lshl_b32 s4, s4, 9
	v_or_b32_e32 v56, v56, v79
	v_mov_b32_e32 v57, v19
	v_lshl_add_u64 v[72:73], v[64:65], 0, v[60:61]
	s_or_b32 s16, s4, 0x8000
	v_lshl_add_u64 v[72:73], v[72:73], 0, v[56:57]
	v_lshl_add_u64 v[56:57], v[64:65], 0, s[16:17]
	global_load_dwordx2 v[100:101], v[62:63], off offset:128
	global_load_dwordx2 v[102:103], v[62:63], off offset:160
	global_load_dwordx2 v[96:97], v[62:63], off offset:192
	global_load_dwordx2 v[94:95], v[62:63], off offset:224
	v_or_b32_e32 v62, 0x70, v78
	v_lshl_add_u64 v[70:71], v[56:57], 0, v[70:71]
	v_lshlrev_b32_e32 v56, 9, v62
	v_lshlrev_b32_e32 v62, 1, v62
	v_and_b32_e32 v144, 56, v62
	v_and_b32_e32 v56, 0x78000, v56
	v_mov_b32_e32 v57, v19
	v_bitop3_b32 v62, v76, v77, v144 bitop3:0x36
	v_or_b32_e32 v62, v62, v80
	v_mov_b32_e32 v63, v19
	v_lshl_add_u64 v[64:65], v[64:65], 0, v[56:57]
	v_lshl_add_u64 v[62:63], v[64:65], 0, v[62:63]
	global_load_dwordx2 v[108:109], v[68:69], off
	global_load_dwordx2 v[104:105], v[72:73], off
	global_load_dwordx2 v[98:99], v[70:71], off
	global_load_dwordx2 v[92:93], v[62:63], off
	v_lshl_add_u64 v[62:63], s[20:21], 0, v[44:45]
	v_lshlrev_b64 v[64:65], 11, v[62:63]
	v_lshl_add_u64 v[58:59], v[58:59], 0, v[64:65]
	v_ashrrev_i32_e32 v64, 8, v62
	v_ashrrev_i32_e32 v65, 31, v64
	v_lshlrev_b64 v[64:65], 19, v[64:65]
	v_lshlrev_b32_e32 v72, 7, v62
; #define GAS __attribute__((address_space(1)))
; #define LAS __attribute__((address_space(3)))
; #define WG_BAR() asm volatile("s_waitcnt lgkmcnt(0)\n\ts_barrier" ::: "memory")
; #define MFMA16(a, b, c) __builtin_amdgcn_mfma_f32_16x16x32_bf16((a), (b), (c), 0, 0, 0)
; __device__ __forceinline__ void hgrn_b3(Frame& F, float* rso) {
;     ...
;         for (int mi = 0; mi < 2; ++mi) { const int t = 32 * w + 16 * mi + r; const size_t rowoff = (grow0 + t) * DM + h * 128;
; #pragma unroll
;             for (int tn = 0; tn < 8; ++tn) { olr[mi][tn] = *(const GAS v2u*)(OL + rowoff + 16 * tn + 4 * g); ggr[mi][tn] = *(const GAS v2u*)(GH + wt_off((int)(grow0 + t), h * 128 + 16 * tn + 4 * g, DM)); } }
; #pragma unroll
;         for (int i = 0; i < 8; ++i) { const int ch = tid + 512 * i, row = ch >> 4, c16 = ch & 15; *(LAS v4u*)(L + B3_Q + row * P272 + c16 * 16) = stq[i]; }
; #pragma unroll
;         for (int i = 0; i < 4; ++i) { const int ch = tid + 512 * i, row = ch >> 4, c16 = ch & 15; *(LAS v4u*)(L + B3_S + row * P272 + c16 * 16) = sts[i]; }
;         WG_BAR();
; #pragma unroll
;         for (int mi = 0; mi < 2; ++mi) {
;             const int t = 32 * w + 16 * mi + r;
;             bf16x8 qa[4];
; #pragma unroll
;             for (int ks = 0; ks < 4; ++ks) qa[ks] = ldfrag(L + B3_Q, t, P272, ks, g);
;             float ss = 0.f;
; #pragma unroll
;             for (int tn = 0; tn < 8; ++tn) {
;                 f32x4 a = (f32x4){0.f, 0.f, 0.f, 0.f};
; #pragma unroll
;                 for (int ks = 0; ks < 4; ++ks) a = MFMA16(ldfrag(L + B3_S, 16 * tn + r, P272, ks, g), qa[ks], a);
	v_lshlrev_b32_e32 v63, 6, v62
	v_lshlrev_b32_e32 v62, 2, v62
	v_and_b32_e32 v68, 0x4000, v72
	v_mov_b32_e32 v69, v19
	v_and_b32_e32 v146, 0x3c0, v63
	v_and_b32_e32 v147, 32, v62
	v_lshl_add_u64 v[62:63], s[12:13], 0, v[64:65]
	v_lshl_add_u64 v[70:71], v[62:63], 0, v[68:69]
	v_and_b32_e32 v151, 0x3800, v72
	v_bitop3_b32 v72, v146, v147, v149 bitop3:0x36
	v_lshl_add_u64 v[64:65], v[70:71], 0, v[18:19]
	v_or_b32_e32 v72, v72, v151
	v_mov_b32_e32 v73, v19
	v_or_b32_e32 v62, v146, v130
	v_lshl_add_u64 v[74:75], v[64:65], 0, v[72:73]
	v_or3_b32 v73, v146, v148, v147
	v_or3_b32 v62, v62, v147, v151
	v_mov_b32_e32 v63, v19
	v_or3_b32 v106, v151, v73, s0
	v_mov_b32_e32 v107, v19
	v_or_b32_e32 v72, 0x400, v72
	v_mov_b32_e32 v73, v19
	v_lshl_add_u64 v[68:69], v[64:65], 0, v[62:63]
	v_lshl_add_u64 v[78:79], v[64:65], 0, v[106:107]
	v_lshl_add_u64 v[64:65], v[64:65], 0, v[72:73]
	global_load_dwordx2 v[88:89], v[58:59], off
	global_load_dwordx2 v[84:85], v[58:59], off offset:32
	global_load_dwordx2 v[80:81], v[58:59], off offset:64
	global_load_dwordx2 v[76:77], v[58:59], off offset:96
	global_load_dwordx2 v[90:91], v[68:69], off
	global_load_dwordx2 v[86:87], v[74:75], off
	global_load_dwordx2 v[82:83], v[78:79], off
	s_nop 0
	global_load_dwordx2 v[78:79], v[64:65], off
	v_lshl_add_u64 v[64:65], v[70:71], 0, v[66:67]
	v_lshl_add_u64 v[66:67], v[64:65], 0, v[62:63]
	v_bitop3_b32 v62, v146, v147, v145 bitop3:0x36
	v_or_b32_e32 v62, v62, v151
	v_lshl_add_u64 v[64:65], v[70:71], 0, v[60:61]
	v_lshl_add_u64 v[114:115], v[64:65], 0, v[62:63]
	v_lshl_add_u64 v[62:63], v[70:71], 0, s[16:17]
	v_lshl_add_u64 v[106:107], v[62:63], 0, v[106:107]
	global_load_dwordx2 v[72:73], v[58:59], off offset:128
	global_load_dwordx2 v[68:69], v[58:59], off offset:160
	global_load_dwordx2 v[64:65], v[58:59], off offset:192
	global_load_dwordx2 v[62:63], v[58:59], off offset:224
	v_bitop3_b32 v58, v146, v147, v144 bitop3:0x36
	v_or3_b32 v58, v151, v58, s0
	v_mov_b32_e32 v59, v19
	v_lshl_add_u64 v[70:71], v[70:71], 0, v[56:57]
	v_lshl_add_u64 v[58:59], v[70:71], 0, v[58:59]
	global_load_dwordx2 v[74:75], v[66:67], off
	global_load_dwordx2 v[70:71], v[114:115], off
	s_nop 0
	global_load_dwordx2 v[66:67], v[106:107], off
	s_nop 0
	global_load_dwordx2 v[58:59], v[58:59], off
	v_add_u32_e32 v106, v25, v131
	s_waitcnt vmcnt(43)
	ds_write_b128 v106, v[2:5]
	v_add_u32_e32 v2, v25, v132
	s_waitcnt vmcnt(42)
	ds_write_b128 v2, v[6:9]
	v_add_u32_e32 v2, v25, v133
	s_waitcnt vmcnt(41)
	ds_write_b128 v2, v[10:13]
	v_add_u32_e32 v2, v25, v134
	s_waitcnt vmcnt(40)
	ds_write_b128 v2, v[14:17]
	s_waitcnt vmcnt(39)
	ds_write_b128 v136, v[152:155]
	s_waitcnt vmcnt(38)
	ds_write_b128 v137, v[156:159]
	s_waitcnt vmcnt(37)
	ds_write_b128 v138, v[162:165]
	s_waitcnt vmcnt(36)
	ds_write_b128 v139, v[166:169]
	v_add_u32_e32 v2, v129, v131
	s_waitcnt vmcnt(35)
	ds_write_b128 v2, v[170:173]
	v_add_u32_e32 v2, v129, v132
	s_waitcnt vmcnt(34)
	ds_write_b128 v2, v[174:177]
	v_add_u32_e32 v2, v129, v133
	s_waitcnt vmcnt(33)
	ds_write_b128 v2, v[178:181]
	v_add_u32_e32 v2, v129, v134
	v_and_b32_e32 v3, 64, v140
	s_waitcnt vmcnt(32)
	ds_write_b128 v2, v[182:185]
	v_xor_b32_e32 v2, 16, v140
	v_add_u32_e32 v3, 64, v3
	v_cmp_lt_i32_e64 s[6:7], v2, v3
	s_waitcnt lgkmcnt(0)
	s_barrier
	v_add_u32_e32 v151, s20, v22
	v_ashrrev_i32_e32 v106, 8, v151
	v_cndmask_b32_e64 v2, v140, v2, s[6:7]
	v_lshlrev_b32_e32 v147, 2, v2
	v_xor_b32_e32 v2, 32, v140
	v_cmp_lt_i32_e64 s[6:7], v2, v3
	v_ashrrev_i32_e32 v107, 31, v106
	v_lshlrev_b64 v[106:107], 19, v[106:107]
	v_cndmask_b32_e64 v2, v140, v2, s[6:7]
	v_lshlrev_b32_e32 v146, 2, v2
	ds_read_b128 v[6:9], v141
	ds_read_b128 v[2:5], v141 offset:64
	ds_read_b128 v[152:155], v142
	ds_read_b128 v[14:17], v141 offset:128
	ds_read_b128 v[10:13], v141 offset:192
	ds_read_b128 v[156:159], v142 offset:64
	ds_read_b128 v[162:165], v142 offset:128
	s_waitcnt lgkmcnt(4)
	v_mfma_f32_16x16x32_bf16 v[152:155], v[152:155], v[6:9], 0
	ds_read_b128 v[166:169], v142 offset:192
	v_lshlrev_b32_e32 v161, 7, v151
	v_and_b32_e32 v114, 0x4000, v161
	s_waitcnt lgkmcnt(2)
	v_mfma_f32_16x16x32_bf16 v[152:155], v[156:159], v[2:5], v[152:155]
	v_mov_b32_e32 v115, v19
	v_lshl_add_u64 v[106:107], s[14:15], 0, v[106:107]
	v_lshlrev_b32_e32 v156, 6, v151
	s_waitcnt lgkmcnt(1)
	v_mfma_f32_16x16x32_bf16 v[152:155], v[162:165], v[14:17], v[152:155]
	v_lshl_add_u64 v[106:107], v[106:107], 0, v[114:115]
	s_waitcnt vmcnt(31)
	v_lshlrev_b32_e32 v114, 16, v116
	v_and_b32_e32 v115, 0xffff0000, v116
	s_waitcnt lgkmcnt(0)
	v_mfma_f32_16x16x32_bf16 v[152:155], v[166:169], v[10:13], v[152:155]
	v_and_b32_e32 v182, 0x3c0, v156
	s_waitcnt vmcnt(27)
	v_lshlrev_b32_e32 v156, 16, v122
	v_and_b32_e32 v157, 0xffff0000, v122
	v_lshlrev_b32_e32 v116, 16, v117
	v_and_b32_e32 v117, 0xffff0000, v117
	s_nop 1
	v_pk_add_f32 v[152:153], v[152:153], v[114:115]
	v_pk_add_f32 v[162:163], v[154:155], v[116:117]
	v_pk_mul_f32 v[114:115], v[152:153], v[152:153]
	v_pk_mul_f32 v[152:153], v[152:153], v[156:157]
	ds_read_b128 v[156:159], v142 offset:4352
	v_cvt_pk_bf16_f32 v122, v152, v153
	ds_read_b128 v[152:155], v142 offset:4416
	v_lshlrev_b32_e32 v164, 16, v123
	v_and_b32_e32 v165, 0xffff0000, v123
	v_pk_mul_f32 v[116:117], v[162:163], v[162:163]
	v_pk_mul_f32 v[166:167], v[162:163], v[164:165]
	ds_read_b128 v[162:165], v142 offset:4480
	s_waitcnt lgkmcnt(2)
	v_mfma_f32_16x16x32_bf16 v[156:159], v[156:159], v[6:9], 0
	v_cvt_pk_bf16_f32 v123, v166, v167
	ds_read_b128 v[166:169], v142 offset:4544
	v_lshlrev_b32_e32 v151, 2, v151
	s_waitcnt lgkmcnt(2)
; #define GAS __attribute__((address_space(1)))
; __device__ __forceinline__ unsigned pk2(float lo, float hi) { f32x2 v = {lo, hi}; bf16x2_t b = __builtin_convertvector(v, bf16x2_t); return __builtin_bit_cast(unsigned, b); }
; __device__ __forceinline__ float bflo(unsigned w) { return __uint_as_float(w << 16); }
; __device__ __forceinline__ float bfhi(unsigned w) { return __uint_as_float(w & 0xffff0000u); }
; #define MFMA16(a, b, c) __builtin_amdgcn_mfma_f32_16x16x32_bf16((a), (b), (c), 0, 0, 0)
; __device__ __forceinline__ void hgrn_b3(Frame& F, float* rso) {
;     ...
;             for (int tn = 0; tn < 8; ++tn) {
;                 f32x4 a = (f32x4){0.f, 0.f, 0.f, 0.f};
; #pragma unroll
;                 for (int ks = 0; ks < 4; ++ks) a = MFMA16(ldfrag(L + B3_S, 16 * tn + r, P272, ks, g), qa[ks], a);
;                 const v2u ol = olr[mi][tn], gg = ggr[mi][tn];
;                 const float o0 = a[0] + bflo(ol.x), o1 = a[1] + bfhi(ol.x), o2 = a[2] + bflo(ol.y), o3 = a[3] + bfhi(ol.y);
;                 ss += (o0 * o0 + o1 * o1) + (o2 * o2 + o3 * o3);
;                 *(GAS v2u*)(A3 + wt_off((int)(grow0 + t), h * 128 + 16 * tn + 4 * g, DM)) = (v2u){pk2(o0 * bflo(gg.x), o1 * bfhi(gg.x)), pk2(o2 * bflo(gg.y), o3 * bfhi(gg.y))};
;             }
	v_mfma_f32_16x16x32_bf16 v[152:155], v[152:155], v[2:5], v[156:159]
	v_and_b32_e32 v183, 32, v151
	v_or_b32_e32 v151, v182, v130
	v_and_b32_e32 v161, 0x3800, v161
	s_waitcnt lgkmcnt(1)
	v_mfma_f32_16x16x32_bf16 v[152:155], v[162:165], v[14:17], v[152:155]
	v_or3_b32 v170, v151, v183, v161
	v_mov_b32_e32 v171, v19
	v_lshl_add_u64 v[172:173], v[106:107], 0, v[18:19]
	s_waitcnt lgkmcnt(0)
	v_mfma_f32_16x16x32_bf16 v[152:155], v[166:169], v[10:13], v[152:155]
	v_lshl_add_u64 v[156:157], v[172:173], 0, v[170:171]
	global_store_dwordx2 v[156:157], v[122:123], off
	v_lshlrev_b32_e32 v122, 16, v124
	v_and_b32_e32 v123, 0xffff0000, v124
	s_waitcnt vmcnt(27)
	v_lshlrev_b32_e32 v156, 16, v126
	s_nop 1
	v_pk_add_f32 v[152:153], v[152:153], v[122:123]
	v_and_b32_e32 v157, 0xffff0000, v126
	v_pk_mul_f32 v[122:123], v[152:153], v[152:153]
	v_pk_mul_f32 v[152:153], v[152:153], v[156:157]
	ds_read_b128 v[156:159], v142 offset:8704
	ds_read_b128 v[162:165], v142 offset:8768
	v_lshlrev_b32_e32 v124, 16, v125
	v_and_b32_e32 v125, 0xffff0000, v125
	v_cvt_pk_bf16_f32 v126, v152, v153
	v_pk_add_f32 v[166:167], v[154:155], v[124:125]
	ds_read_b128 v[152:155], v142 offset:8832
	s_waitcnt lgkmcnt(2)
	v_mfma_f32_16x16x32_bf16 v[156:159], v[156:159], v[6:9], 0
	v_lshlrev_b32_e32 v168, 16, v127
	v_and_b32_e32 v169, 0xffff0000, v127
	v_pk_mul_f32 v[124:125], v[166:167], v[166:167]
	v_pk_mul_f32 v[174:175], v[166:167], v[168:169]
	ds_read_b128 v[166:169], v142 offset:8896
	s_waitcnt lgkmcnt(2)
	v_mfma_f32_16x16x32_bf16 v[156:159], v[162:165], v[2:5], v[156:159]
	v_bitop3_b32 v151, v182, v183, v149 bitop3:0x36
	v_cvt_pk_bf16_f32 v127, v174, v175
	v_or_b32_e32 v174, v151, v161
	s_waitcnt lgkmcnt(1)
	v_mfma_f32_16x16x32_bf16 v[152:155], v[152:155], v[14:17], v[156:159]
	v_mov_b32_e32 v175, v19
	ds_read_b128 v[162:165], v142 offset:13120
	v_or3_b32 v151, v182, v148, v183
	s_waitcnt lgkmcnt(1)
	v_mfma_f32_16x16x32_bf16 v[152:155], v[166:169], v[10:13], v[152:155]
	v_lshl_add_u64 v[156:157], v[172:173], 0, v[174:175]
	global_store_dwordx2 v[156:157], v[126:127], off
	v_lshlrev_b32_e32 v126, 16, v118
	v_and_b32_e32 v127, 0xffff0000, v118
	s_waitcnt vmcnt(27)
	v_lshlrev_b32_e32 v156, 16, v120
	s_nop 1
	v_pk_add_f32 v[152:153], v[152:153], v[126:127]
	v_and_b32_e32 v157, 0xffff0000, v120
	v_pk_mul_f32 v[126:127], v[152:153], v[152:153]
	v_pk_mul_f32 v[152:153], v[152:153], v[156:157]
	ds_read_b128 v[156:159], v142 offset:13056
	v_lshlrev_b32_e32 v118, 16, v119
	v_and_b32_e32 v119, 0xffff0000, v119
	v_cvt_pk_bf16_f32 v120, v152, v153
	v_pk_add_f32 v[166:167], v[154:155], v[118:119]
	ds_read_b128 v[152:155], v142 offset:13184
	s_waitcnt lgkmcnt(1)
	v_mfma_f32_16x16x32_bf16 v[156:159], v[156:159], v[6:9], 0
	v_lshlrev_b32_e32 v168, 16, v121
	v_and_b32_e32 v169, 0xffff0000, v121
	v_pk_mul_f32 v[118:119], v[166:167], v[166:167]
	v_pk_mul_f32 v[176:177], v[166:167], v[168:169]
	ds_read_b128 v[166:169], v142 offset:13248
	v_mfma_f32_16x16x32_bf16 v[156:159], v[162:165], v[2:5], v[156:159]
	v_cvt_pk_bf16_f32 v121, v176, v177
	v_or3_b32 v176, v161, v151, s0
	v_mov_b32_e32 v177, v19
	s_waitcnt lgkmcnt(1)
	v_mfma_f32_16x16x32_bf16 v[152:155], v[152:155], v[14:17], v[156:159]
	s_waitcnt vmcnt(26)
	v_lshlrev_b32_e32 v162, 16, v112
	v_and_b32_e32 v163, 0xffff0000, v112
	v_lshlrev_b32_e32 v180, 16, v113
	v_lshl_add_u64 v[156:157], v[172:173], 0, v[176:177]
	s_waitcnt lgkmcnt(0)
	v_mfma_f32_16x16x32_bf16 v[152:155], v[166:169], v[10:13], v[152:155]
	global_store_dwordx2 v[156:157], v[120:121], off
	ds_read_b128 v[156:159], v142 offset:17408
	v_lshlrev_b32_e32 v120, 16, v110
	v_and_b32_e32 v121, 0xffff0000, v110
	v_lshlrev_b32_e32 v110, 16, v111
	s_nop 2
	v_pk_add_f32 v[152:153], v[152:153], v[120:121]
	v_and_b32_e32 v111, 0xffff0000, v111
	v_pk_mul_f32 v[120:121], v[152:153], v[152:153]
	v_pk_mul_f32 v[152:153], v[152:153], v[162:163]
	ds_read_b128 v[162:165], v142 offset:17472
	v_cvt_pk_bf16_f32 v166, v152, v153
	v_pk_add_f32 v[168:169], v[154:155], v[110:111]
	ds_read_b128 v[152:155], v142 offset:17536
	s_waitcnt lgkmcnt(2)
	v_mfma_f32_16x16x32_bf16 v[156:159], v[156:159], v[6:9], 0
	v_and_b32_e32 v181, 0xffff0000, v113
	ds_read_b128 v[110:113], v142 offset:17600
	v_pk_mul_f32 v[178:179], v[168:169], v[168:169]
	s_waitcnt lgkmcnt(2)
	v_mfma_f32_16x16x32_bf16 v[156:159], v[162:165], v[2:5], v[156:159]
	v_mul_f32_e64 v162, v168, v180
	v_mul_f32_e64 v163, v169, v181
	s_waitcnt vmcnt(21)
	v_and_b32_e32 v151, 0xffff0000, v104
	v_cvt_pk_bf16_f32 v167, v162, v163
	s_waitcnt lgkmcnt(1)
	v_mfma_f32_16x16x32_bf16 v[152:155], v[152:155], v[14:17], v[156:159]
	v_or_b32_e32 v162, 0x400, v174
	v_mov_b32_e32 v163, v19
	s_lshl_b64 s[4:5], s[20:21], 2
	s_waitcnt lgkmcnt(0)
	v_mfma_f32_16x16x32_bf16 v[110:113], v[110:113], v[10:13], v[152:155]
	v_lshl_add_u64 v[156:157], v[172:173], 0, v[162:163]
	global_store_dwordx2 v[156:157], v[166:167], off
	ds_read_b128 v[156:159], v142 offset:21824
	v_lshlrev_b32_e32 v152, 16, v100
	v_and_b32_e32 v153, 0xffff0000, v100
	s_nop 2
	v_pk_add_f32 v[110:111], v[110:111], v[152:153]
	v_lshlrev_b32_e32 v152, 16, v108
	v_and_b32_e32 v153, 0xffff0000, v108
	v_pk_mul_f32 v[166:167], v[110:111], v[110:111]
	v_pk_mul_f32 v[110:111], v[110:111], v[152:153]
	ds_read_b128 v[152:155], v142 offset:21760
	v_lshlrev_b32_e32 v100, 16, v101
	v_and_b32_e32 v101, 0xffff0000, v101
	v_cvt_pk_bf16_f32 v168, v110, v111
	v_pk_add_f32 v[100:101], v[112:113], v[100:101]
	ds_read_b128 v[110:113], v142 offset:21888
	ds_read_b128 v[162:165], v142 offset:21952
	s_waitcnt lgkmcnt(2)
; #define GAS __attribute__((address_space(1)))
; __device__ __forceinline__ unsigned pk2(float lo, float hi) { f32x2 v = {lo, hi}; bf16x2_t b = __builtin_convertvector(v, bf16x2_t); return __builtin_bit_cast(unsigned, b); }
; __device__ __forceinline__ float bflo(unsigned w) { return __uint_as_float(w << 16); }
; __device__ __forceinline__ float bfhi(unsigned w) { return __uint_as_float(w & 0xffff0000u); }
; #define MFMA16(a, b, c) __builtin_amdgcn_mfma_f32_16x16x32_bf16((a), (b), (c), 0, 0, 0)
; __device__ __forceinline__ void hgrn_b3(Frame& F, float* rso) {
;     ...
;             for (int tn = 0; tn < 8; ++tn) {
;                 f32x4 a = (f32x4){0.f, 0.f, 0.f, 0.f};
; #pragma unroll
;                 for (int ks = 0; ks < 4; ++ks) a = MFMA16(ldfrag(L + B3_S, 16 * tn + r, P272, ks, g), qa[ks], a);
;                 const v2u ol = olr[mi][tn], gg = ggr[mi][tn];
;                 const float o0 = a[0] + bflo(ol.x), o1 = a[1] + bfhi(ol.x), o2 = a[2] + bflo(ol.y), o3 = a[3] + bfhi(ol.y);
;                 ss += (o0 * o0 + o1 * o1) + (o2 * o2 + o3 * o3);
;                 *(GAS v2u*)(A3 + wt_off((int)(grow0 + t), h * 128 + 16 * tn + 4 * g, DM)) = (v2u){pk2(o0 * bflo(gg.x), o1 * bfhi(gg.x)), pk2(o2 * bflo(gg.y), o3 * bfhi(gg.y))};
;             }
;             ss += __shfl_xor(ss, 16); ss += __shfl_xor(ss, 32);
;             if (g == 0) atomicAdd(rso + grow0 + t, ss);
	v_mfma_f32_16x16x32_bf16 v[152:155], v[152:155], v[6:9], 0
	v_lshlrev_b32_e32 v108, 16, v109
	v_and_b32_e32 v109, 0xffff0000, v109
	v_pk_mul_f32 v[172:173], v[100:101], v[100:101]
	v_mfma_f32_16x16x32_bf16 v[152:155], v[156:159], v[2:5], v[152:155]
	v_mul_f32_e64 v100, v100, v108
	v_mul_f32_e64 v101, v101, v109
	v_lshlrev_b32_e32 v156, 16, v105
	v_cvt_pk_bf16_f32 v169, v100, v101
	s_waitcnt lgkmcnt(1)
	v_mfma_f32_16x16x32_bf16 v[108:111], v[110:113], v[14:17], v[152:155]
	v_bitop3_b32 v100, v150, s26, v143 bitop3:0xc8
	v_mov_b32_e32 v101, v19
	v_lshl_add_u64 v[112:113], v[106:107], 0, v[100:101]
	s_waitcnt lgkmcnt(0)
	v_mfma_f32_16x16x32_bf16 v[108:111], v[162:165], v[10:13], v[108:111]
	v_lshl_add_u64 v[112:113], v[112:113], 0, v[170:171]
	global_store_dwordx2 v[112:113], v[168:169], off
	v_lshlrev_b32_e32 v112, 16, v102
	v_and_b32_e32 v113, 0xffff0000, v102
	v_lshlrev_b32_e32 v150, 16, v104
	s_nop 2
	v_pk_add_f32 v[108:109], v[108:109], v[112:113]
	v_lshlrev_b32_e32 v102, 16, v103
	v_pk_mul_f32 v[112:113], v[108:109], v[108:109]
	v_pk_mul_f32 v[108:109], v[108:109], v[150:151]
	ds_read_b128 v[150:153], v142 offset:26112
	v_and_b32_e32 v103, 0xffff0000, v103
	v_cvt_pk_bf16_f32 v158, v108, v109
	v_pk_add_f32 v[154:155], v[110:111], v[102:103]
	ds_read_b128 v[108:111], v142 offset:26176
	v_and_b32_e32 v157, 0xffff0000, v105
	ds_read_b128 v[102:105], v142 offset:26240
	s_waitcnt lgkmcnt(2)
	v_mfma_f32_16x16x32_bf16 v[150:153], v[150:153], v[6:9], 0
	v_mul_f32_e64 v162, v154, v154
	v_mul_f32_e64 v163, v155, v155
	v_pk_mul_f32 v[154:155], v[154:155], v[156:157]
	s_add_u32 s6, s92, s4
	v_cvt_pk_bf16_f32 v159, v154, v155
	ds_read_b128 v[154:157], v142 offset:26304
	s_waitcnt lgkmcnt(2)
	v_mfma_f32_16x16x32_bf16 v[108:111], v[108:111], v[2:5], v[150:153]
	s_addc_u32 s7, s93, s5
	s_waitcnt lgkmcnt(1)
	v_mfma_f32_16x16x32_bf16 v[102:105], v[102:105], v[14:17], v[108:111]
	v_bitop3_b32 v150, v182, v183, v145 bitop3:0x36
	v_or_b32_e32 v150, v150, v161
	v_mov_b32_e32 v151, v19
	s_waitcnt lgkmcnt(0)
	v_mfma_f32_16x16x32_bf16 v[102:105], v[154:157], v[10:13], v[102:105]
	v_lshl_add_u64 v[108:109], v[106:107], 0, v[60:61]
	v_lshl_add_u64 v[108:109], v[108:109], 0, v[150:151]
	global_store_dwordx2 v[108:109], v[158:159], off
	v_lshlrev_b32_e32 v108, 16, v96
	v_and_b32_e32 v109, 0xffff0000, v96
	s_nop 2
	v_pk_add_f32 v[102:103], v[102:103], v[108:109]
	ds_read_b128 v[108:111], v142 offset:30464
	s_waitcnt vmcnt(23)
	v_lshlrev_b32_e32 v150, 16, v98
	v_and_b32_e32 v151, 0xffff0000, v98
	v_pk_mul_f32 v[154:155], v[102:103], v[102:103]
	v_pk_mul_f32 v[102:103], v[102:103], v[150:151]
	ds_read_b128 v[150:153], v142 offset:30528
	v_cvt_pk_bf16_f32 v96, v102, v103
	v_lshlrev_b32_e32 v102, 16, v97
	v_and_b32_e32 v103, 0xffff0000, v97
	v_pk_add_f32 v[156:157], v[104:105], v[102:103]
	ds_read_b128 v[102:105], v142 offset:30592
	s_waitcnt lgkmcnt(2)
	v_mfma_f32_16x16x32_bf16 v[6:9], v[108:111], v[6:9], 0
	ds_read_b128 v[108:111], v142 offset:30656
	v_lshlrev_b32_e32 v98, 16, v99
	v_and_b32_e32 v99, 0xffff0000, v99
	s_waitcnt lgkmcnt(2)
	v_mfma_f32_16x16x32_bf16 v[2:5], v[150:153], v[2:5], v[6:9]
	v_mul_f32_e64 v158, v156, v156
	v_mul_f32_e64 v159, v157, v157
	s_waitcnt lgkmcnt(1)
	v_mfma_f32_16x16x32_bf16 v[2:5], v[102:105], v[14:17], v[2:5]
	v_mul_f32_e64 v6, v156, v98
	v_mul_f32_e64 v7, v157, v99
	s_waitcnt vmcnt(22)
	v_lshlrev_b32_e32 v8, 16, v92
	v_cvt_pk_bf16_f32 v97, v6, v7
	s_waitcnt lgkmcnt(0)
	v_mfma_f32_16x16x32_bf16 v[2:5], v[108:111], v[10:13], v[2:5]
	v_lshl_add_u64 v[6:7], v[106:107], 0, s[16:17]
	v_lshl_add_u64 v[6:7], v[6:7], 0, v[176:177]
	global_store_dwordx2 v[6:7], v[96:97], off
	v_lshlrev_b32_e32 v6, 16, v94
	v_and_b32_e32 v7, 0xffff0000, v94
	s_nop 2
	v_pk_add_f32 v[2:3], v[2:3], v[6:7]
	v_and_b32_e32 v9, 0xffff0000, v92
	v_pk_mul_f32 v[6:7], v[2:3], v[2:3]
	v_pk_mul_f32 v[2:3], v[2:3], v[8:9]
	v_add_f32_e32 v9, v122, v123
	v_add_f32_e32 v10, v124, v125
	v_add_f32_e32 v9, v9, v10
	v_add_f32_e32 v10, v114, v115
	v_add_f32_e32 v11, v116, v117
	v_add_f32_e32 v10, v10, v11
	v_add_f32_e32 v9, v10, v9
	v_add_f32_e32 v10, v126, v127
	v_add_f32_e32 v11, v118, v119
	v_add_f32_e32 v10, v10, v11
	v_add_f32_e32 v9, v9, v10
	v_add_f32_e32 v10, v120, v121
	v_add_f32_e32 v11, v178, v179
	v_add_f32_e32 v10, v10, v11
	v_add_f32_e32 v9, v9, v10
	v_add_f32_e32 v10, v166, v167
	v_add_f32_e32 v11, v172, v173
	v_add_f32_e32 v10, v10, v11
	v_cvt_pk_bf16_f32 v8, v2, v3
	v_lshlrev_b32_e32 v2, 16, v95
	v_and_b32_e32 v3, 0xffff0000, v95
	v_add_f32_e32 v9, v9, v10
	v_add_f32_e32 v10, v112, v113
	v_add_f32_e32 v11, v162, v163
	v_pk_add_f32 v[2:3], v[4:5], v[2:3]
	v_add_f32_e32 v10, v10, v11
	v_pk_mul_f32 v[4:5], v[2:3], v[2:3]
	v_add_f32_e32 v9, v9, v10
	v_add_f32_e32 v10, v154, v155
	v_add_f32_e32 v11, v158, v159
	v_add_f32_e32 v10, v10, v11
	v_add_f32_e32 v6, v6, v7
	v_add_f32_e32 v4, v4, v5
	v_add_f32_e32 v9, v9, v10
	v_add_f32_e32 v4, v6, v4
	v_add_f32_e32 v6, v9, v4
	ds_bpermute_b32 v7, v147, v6
	v_lshlrev_b32_e32 v4, 16, v93
	v_and_b32_e32 v5, 0xffff0000, v93
	v_pk_mul_f32 v[2:3], v[2:3], v[4:5]
	v_mov_b32_e32 v5, v19
	v_cvt_pk_bf16_f32 v9, v2, v3
	v_bitop3_b32 v2, v182, v183, v144 bitop3:0x36
	v_or3_b32 v4, v161, v2, s0
	s_waitcnt lgkmcnt(0)
	v_add_f32_e32 v2, v6, v7
	ds_bpermute_b32 v3, v146, v2
	v_lshl_add_u64 v[6:7], v[106:107], 0, v[56:57]
	v_lshl_add_u64 v[4:5], v[6:7], 0, v[4:5]
	global_store_dwordx2 v[4:5], v[8:9], off
	s_and_saveexec_b64 s[4:5], vcc
	s_cbranch_execz .LBB0_825
	s_waitcnt lgkmcnt(0)
	v_add_f32_e32 v4, v2, v3
	v_lshl_add_u64 v[2:3], v[22:23], 2, s[6:7]
	global_atomic_add_f32 v[2:3], v4, off
